# GEMM phase prologues: first barrier moved behind the issue of K-tile 1's staging loads (vmcnt(8)), both K-tiles in flight together
# baseline (speedup 1.0000x reference)
; #define PG8_STAGE(bufoff, gbase, voff) do { _Pragma("unroll") for (int _i = 0; _i < 2; ++_i) \
;         __builtin_amdgcn_global_load_lds((const unsigned*)((const char*)(gbase) + (voff)[_i]), (PG8_LAS unsigned*)(lds + (bufoff) + ldsw + _i * 8192), 16, 0, 0); } while (0)
; #define PG8_WAIT_V(n) asm volatile("s_waitcnt vmcnt(" #n ")" ::: "memory")
; #define PG8_BAR __builtin_amdgcn_s_barrier()
; template <class Epi, class Sched, bool ALIGN_EPI = false, bool SP2 = false>
; __device__ __forceinline__ void gemm_phase(PG8_LAS unsigned char* lds, const Gemm g, const Sched& S, const Epi& E, const int tid_arg) {
;     ...
;     if constexpr (SP2) {
;         PG8_STAGE(PG8_SB(0, 0), cB, voffB); PG8_STAGE(PG8_SB(0, 1), cB + hstep, voffB); PG8_STAGE(PG8_SA(0, 0), cA, voffA); PG8_STAGE(PG8_SA(0, 1), cA + hstep, voffA);
;         if (wr == 1) PG8_BAR;
;         PG8_WAIT_V(2); PG8_BAR;
;         PG8_STAGE(PG8_SB(1, 0), cB + kstep, voffB); PG8_STAGE(PG8_SA(1, 0), cA + kstep, voffA); PG8_STAGE(PG8_SB(1, 1), cB + hstep + kstep, voffB);
;         PG8_WAIT_V(6); PG8_BAR;
;     } else {
;         PG8_STAGE(PG8_SB(0, 0), cB, voffB); PG8_STAGE(PG8_SA(0, 0), cA, voffA); PG8_STAGE(PG8_SB(0, 1), cB + hstep, voffB); PG8_STAGE(PG8_SA(0, 1), cA + hstep, voffA);
;         if (wr == 1) PG8_BAR;
;         PG8_WAIT_V(4); PG8_BAR;
;         PG8_STAGE(PG8_SB(1, 0), cB + kstep, voffB); PG8_STAGE(PG8_SA(1, 0), cA + kstep, voffA); PG8_STAGE(PG8_SB(1, 1), cB + hstep + kstep, voffB);
;         PG8_WAIT_V(6); PG8_BAR;
;     }
.LBB0_86:
	s_add_u32 s10, s12, 0x8c90000
	s_addc_u32 s11, s13, 0
	s_lshl_b32 s14, s14, 5
	s_and_b32 s20, s14, 0x60
	s_mov_b64 s[14:15], 0x80
	s_add_i32 m0, s27, 0x18000
	v_lshl_add_u64 v[8:9], v[8:9], 0, s[14:15]
	s_lshl_b32 s17, s16, 13
	s_lshl_b32 s21, s20, 7
	global_load_lds_dwordx4 v[8:9], off
	v_lshl_add_u64 v[6:7], v[6:7], 0, s[14:15]
	s_add_i32 m0, s27, 0x1a000
	s_add_i32 s39, s27, 0x8000
	s_add_i32 s40, s27, 0xa000
	global_load_lds_dwordx4 v[6:7], off
	v_lshl_add_u64 v[2:3], v[2:3], 0, s[14:15]
	s_mov_b32 m0, s39
	s_add_u32 s18, s30, 0x40080
	global_load_lds_dwordx4 v[2:3], off
	v_lshl_add_u64 v[2:3], v[4:5], 0, s[14:15]
	s_mov_b32 m0, s40
	s_addc_u32 s19, s31, 0
	global_load_lds_dwordx4 v[2:3], off
	s_add_i32 m0, s27, 0x1c000
	v_lshl_add_u64 v[2:3], s[18:19], 0, v[134:135]
	global_load_lds_dwordx4 v[2:3], off
	v_lshl_add_u64 v[2:3], s[18:19], 0, v[130:131]
	s_add_i32 m0, s27, 0x1e000
	s_cmpk_lt_u32 s7, 0x100
	global_load_lds_dwordx4 v[2:3], off
	v_bfe_u32 v3, v11, 4, 2
	v_and_b32_e32 v2, 15, v11
	v_lshlrev_b32_e32 v4, 4, v3
	v_lshl_or_b32 v146, s16, 6, v2
	v_lshl_or_b32 v2, v2, 6, v4
	v_lshlrev_b32_e32 v4, 2, v11
	v_and_b32_e32 v4, 32, v4
	v_bitop3_b32 v5, v2, s17, v4 bitop3:0xde
	v_bitop3_b32 v147, v2, s21, v4 bitop3:0xde
	v_lshlrev_b32_e32 v2, 14, v15
	v_and_b32_e32 v2, 0xffff8000, v2
	v_lshl_or_b32 v148, v3, 3, s20
	v_lshl_add_u32 v2, v14, 11, v2
	v_and_b32_e32 v3, 1, v15
	v_lshl_or_b32 v2, v3, 6, v2
	v_lshl_add_u32 v138, v16, 1, v2
	v_lshlrev_b32_e32 v2, 14, v10
	v_and_b32_e32 v2, 0xffff8000, v2
	s_waitcnt vmcnt(8)
	s_barrier
	s_waitcnt vmcnt(6)
	v_lshl_add_u32 v2, v12, 11, v2
	v_and_b32_e32 v3, 1, v10
	s_cselect_b64 s[16:17], -1, 0
	v_lshl_or_b32 v2, v3, 6, v2
	s_add_i32 s41, 0, 0x10000
	s_add_i32 s42, 0, 0x14000
	s_sext_i32_i8 s44, s6
	v_mov_b32_e32 v139, v135
	v_lshl_add_u32 v140, v13, 1, v2
	v_mov_b32_e32 v141, v135
	v_mov_b64_e32 v[142:143], 0xb2c
	v_mov_b64_e32 v[144:145], 0xb2b
	v_add_u32_e32 v149, s41, v147
	v_add_u32_e32 v150, s42, v147
	v_add_u32_e32 v151, 0, v5
	s_movk_i32 s43, 0x1600
	s_barrier
	s_branch .LBB0_89

; #define PG8_STAGE(bufoff, gbase, voff) do { _Pragma("unroll") for (int _i = 0; _i < 2; ++_i) \
;         __builtin_amdgcn_global_load_lds((const unsigned*)((const char*)(gbase) + (voff)[_i]), (PG8_LAS unsigned*)(lds + (bufoff) + ldsw + _i * 8192), 16, 0, 0); } while (0)
; #define PG8_WAIT_V(n) asm volatile("s_waitcnt vmcnt(" #n ")" ::: "memory")
; #define PG8_BAR __builtin_amdgcn_s_barrier()
; template <class Epi, class Sched, bool ALIGN_EPI = false, bool SP2 = false>
; __device__ __forceinline__ void gemm_phase(PG8_LAS unsigned char* lds, const Gemm g, const Sched& S, const Epi& E, const int tid_arg) {
;     ...
;     if constexpr (SP2) {
;         PG8_STAGE(PG8_SB(0, 0), cB, voffB); PG8_STAGE(PG8_SB(0, 1), cB + hstep, voffB); PG8_STAGE(PG8_SA(0, 0), cA, voffA); PG8_STAGE(PG8_SA(0, 1), cA + hstep, voffA);
;         if (wr == 1) PG8_BAR;
;         PG8_WAIT_V(2); PG8_BAR;
;         PG8_STAGE(PG8_SB(1, 0), cB + kstep, voffB); PG8_STAGE(PG8_SA(1, 0), cA + kstep, voffA); PG8_STAGE(PG8_SB(1, 1), cB + hstep + kstep, voffB);
;         PG8_WAIT_V(6); PG8_BAR;
;     } else {
;         PG8_STAGE(PG8_SB(0, 0), cB, voffB); PG8_STAGE(PG8_SA(0, 0), cA, voffA); PG8_STAGE(PG8_SB(0, 1), cB + hstep, voffB); PG8_STAGE(PG8_SA(0, 1), cA + hstep, voffA);
;         if (wr == 1) PG8_BAR;
;         PG8_WAIT_V(4); PG8_BAR;
;         PG8_STAGE(PG8_SB(1, 0), cB + kstep, voffB); PG8_STAGE(PG8_SA(1, 0), cA + kstep, voffA); PG8_STAGE(PG8_SB(1, 1), cB + hstep + kstep, voffB);
;         PG8_WAIT_V(6); PG8_BAR;
;     }
.LBB0_246:
	s_add_u32 s20, s4, 0x4780000
	s_addc_u32 s21, s5, 0
	s_add_u32 s22, s4, 0x8880000
	s_mov_b64 s[24:25], 0x80
	s_addc_u32 s23, s5, 0
	s_and_b32 s47, s11, 3
	s_add_i32 m0, s43, 0x18000
	v_lshl_add_u64 v[8:9], v[8:9], 0, s[24:25]
	s_lshl_b32 s11, s13, 13
	s_lshl_b32 s16, s47, 12
	global_load_lds_dwordx4 v[8:9], off
	v_lshl_add_u64 v[6:7], v[6:7], 0, s[24:25]
	s_add_i32 m0, s43, 0x1a000
	s_add_i32 s48, s43, 0x8000
	s_add_i32 s49, s43, 0xa000
	global_load_lds_dwordx4 v[6:7], off
	v_lshl_add_u64 v[2:3], v[2:3], 0, s[24:25]
	s_mov_b32 m0, s48
	s_add_u32 s8, s36, 0xb0080
	global_load_lds_dwordx4 v[2:3], off
	v_lshl_add_u64 v[2:3], v[4:5], 0, s[24:25]
	s_mov_b32 m0, s49
	s_addc_u32 s9, s37, 0
	global_load_lds_dwordx4 v[2:3], off
	s_add_i32 m0, s43, 0x1c000
	v_lshl_add_u64 v[2:3], s[8:9], 0, v[132:133]
	global_load_lds_dwordx4 v[2:3], off
	v_lshl_add_u64 v[2:3], s[8:9], 0, v[136:137]
	s_add_i32 m0, s43, 0x1e000
	s_cmpk_lt_u32 s12, 0x100
	global_load_lds_dwordx4 v[2:3], off
	v_bfe_u32 v2, v10, 4, 2
	v_and_b32_e32 v3, 15, v10
	v_lshlrev_b32_e32 v5, 4, v2
	v_lshl_or_b32 v152, s13, 6, v3
	v_lshl_or_b32 v3, v3, 6, v5
	v_lshlrev_b32_e32 v5, 2, v10
	v_and_b32_e32 v5, 32, v5
	v_lshlrev_b32_e32 v4, 3, v2
	v_bitop3_b32 v6, v3, s11, v5 bitop3:0xde
	v_bitop3_b32 v153, v3, s16, v5 bitop3:0xde
	v_cmp_eq_u32_e64 s[8:9], 0, v2
	v_lshrrev_b32_e32 v3, 1, v11
	v_mul_lo_u32 v2, v13, s10
	s_mov_b32 s11, 0xb000
	v_mad_u64_u32 v[2:3], s[12:13], v3, s11, v[2:3]
	v_or_b32_e32 v2, v2, v12
	s_mov_b64 s[28:29], 0xb0080
	v_add_lshl_u32 v2, v2, v14, 1
	v_mov_b32_e32 v3, v133
	v_lshl_add_u64 v[138:139], v[2:3], 0, s[28:29]
	v_lshrrev_b32_e32 v3, 1, v15
	v_mul_lo_u32 v2, v16, s10
	v_mad_u64_u32 v[2:3], s[10:11], v3, s11, v[2:3]
	s_waitcnt vmcnt(8)
	s_barrier
	s_waitcnt vmcnt(6)
	v_or_b32_e32 v2, v2, v17
	s_cselect_b64 s[26:27], -1, 0
	v_add_lshl_u32 v2, v2, v18, 1
	v_mov_b32_e32 v3, v133
	s_add_i32 s50, 0, 0x10000
	s_add_i32 s51, 0, 0x14000
	v_lshl_or_b32 v154, s47, 5, v4
	v_or_b32_e32 v155, 16, v152
	v_or_b32_e32 v156, 32, v152
	v_or_b32_e32 v157, 48, v152
	v_add_u32_e32 v158, 0x80, v152
	v_add_u32_e32 v159, 0x90, v152
	v_add_u32_e32 v160, 0xa0, v152
	v_add_u32_e32 v161, 0xb0, v152
	v_lshl_add_u64 v[140:141], v[2:3], 0, s[28:29]
	v_mov_b64_e32 v[142:143], 0x200
	v_mov_b64_e32 v[144:145], 0x1ff
	v_add_u32_e32 v162, s50, v153
	v_add_u32_e32 v163, s51, v153
	v_add_u32_e32 v164, 0, v6
	s_mov_b32 s52, 0
	s_barrier
	s_branch .LBB0_249

; #define PG8_STAGE(bufoff, gbase, voff) do { _Pragma("unroll") for (int _i = 0; _i < 2; ++_i) \
;         __builtin_amdgcn_global_load_lds((const unsigned*)((const char*)(gbase) + (voff)[_i]), (PG8_LAS unsigned*)(lds + (bufoff) + ldsw + _i * 8192), 16, 0, 0); } while (0)
; #define PG8_WAIT_V(n) asm volatile("s_waitcnt vmcnt(" #n ")" ::: "memory")
; #define PG8_BAR __builtin_amdgcn_s_barrier()
; template <class Epi, class Sched, bool ALIGN_EPI = false, bool SP2 = false>
; __device__ __forceinline__ void gemm_phase(PG8_LAS unsigned char* lds, const Gemm g, const Sched& S, const Epi& E, const int tid_arg) {
;     ...
;     if constexpr (SP2) {
;         PG8_STAGE(PG8_SB(0, 0), cB, voffB); PG8_STAGE(PG8_SB(0, 1), cB + hstep, voffB); PG8_STAGE(PG8_SA(0, 0), cA, voffA); PG8_STAGE(PG8_SA(0, 1), cA + hstep, voffA);
;         if (wr == 1) PG8_BAR;
;         PG8_WAIT_V(2); PG8_BAR;
;         PG8_STAGE(PG8_SB(1, 0), cB + kstep, voffB); PG8_STAGE(PG8_SA(1, 0), cA + kstep, voffA); PG8_STAGE(PG8_SB(1, 1), cB + hstep + kstep, voffB);
;         PG8_WAIT_V(6); PG8_BAR;
;     } else {
;         PG8_STAGE(PG8_SB(0, 0), cB, voffB); PG8_STAGE(PG8_SA(0, 0), cA, voffA); PG8_STAGE(PG8_SB(0, 1), cB + hstep, voffB); PG8_STAGE(PG8_SA(0, 1), cA + hstep, voffA);
;         if (wr == 1) PG8_BAR;
;         PG8_WAIT_V(4); PG8_BAR;
;         PG8_STAGE(PG8_SB(1, 0), cB + kstep, voffB); PG8_STAGE(PG8_SA(1, 0), cA + kstep, voffA); PG8_STAGE(PG8_SB(1, 1), cB + hstep + kstep, voffB);
;         PG8_WAIT_V(6); PG8_BAR;
;     }
.LBB0_353:
	s_add_u32 s59, s18, 0x8c90000
	s_addc_u32 s60, s19, 0
	s_add_u32 s20, s18, 0x15290000
	s_addc_u32 s21, s19, 0
	v_readlane_b32 s0, v250, 6
	v_bfe_u32 v20, v13, 4, 2
	s_add_u32 s8, s18, s0
	v_and_b32_e32 v19, 15, v13
	v_lshlrev_b32_e32 v2, 4, v20
	v_lshlrev_b32_e32 v13, 2, v13
	s_addc_u32 s9, s19, 0
	s_and_b32 s7, s7, 3
	v_lshl_or_b32 v166, s22, 6, v19
	v_lshl_or_b32 v19, v19, 6, v2
	s_lshl_b32 s11, s22, 13
	v_and_b32_e32 v13, 32, v13
	s_add_i32 m0, s55, 0x18000
	v_lshl_add_u64 v[10:11], v[10:11], 0, s[76:77]
	v_bitop3_b32 v22, v19, s11, v13 bitop3:0xde
	s_lshl_b32 s11, s7, 12
	global_load_lds_dwordx4 v[10:11], off
	v_lshl_add_u64 v[8:9], v[8:9], 0, s[76:77]
	s_add_i32 m0, s55, 0x1a000
	s_add_i32 s61, s55, 0x8000
	s_add_i32 s62, s55, 0xa000
	global_load_lds_dwordx4 v[8:9], off
	v_lshl_add_u64 v[4:5], v[4:5], 0, s[76:77]
	s_mov_b32 m0, s61
	s_add_u32 s22, s36, 0x40080
	global_load_lds_dwordx4 v[4:5], off
	v_lshl_add_u64 v[4:5], v[6:7], 0, s[76:77]
	s_mov_b32 m0, s62
	s_addc_u32 s23, s37, 0
	global_load_lds_dwordx4 v[4:5], off
	s_add_i32 m0, s55, 0x1c000
	v_lshl_add_u64 v[4:5], s[22:23], 0, v[134:135]
	global_load_lds_dwordx4 v[4:5], off
	v_lshl_add_u64 v[4:5], s[22:23], 0, v[138:139]
	s_add_i32 m0, s55, 0x1e000
	s_cmpk_lt_u32 s6, 0x100
	global_load_lds_dwordx4 v[4:5], off
	v_lshlrev_b32_e32 v21, 3, v20
	s_cselect_b64 s[22:23], -1, 0
	s_cmp_eq_u32 s7, 0
	v_lshl_or_b32 v168, s7, 5, v21
	s_cselect_b64 s[6:7], -1, 0
	v_cmp_gt_u32_e32 vcc, 2, v20
	s_and_b64 s[24:25], s[6:7], vcc
	v_lshl_add_u64 v[4:5], s[8:9], 0, v[2:3]
	s_mov_b64 s[6:7], 0x8880000
	v_lshlrev_b32_e32 v2, 5, v20
	v_lshl_add_u64 v[146:147], v[4:5], 0, s[6:7]
	v_lshl_add_u64 v[4:5], s[18:19], 0, v[2:3]
	v_lshlrev_b32_e32 v2, 14, v12
	s_mov_b64 s[6:7], 0x19490000
	v_and_b32_e32 v2, 0xffff8000, v2
	v_lshl_add_u64 v[148:149], v[4:5], 0, s[6:7]
	v_lshl_add_u32 v2, v14, 11, v2
	v_and_b32_e32 v4, 1, v12
	v_lshl_or_b32 v2, v4, 6, v2
	v_lshl_add_u32 v150, v15, 1, v2
	v_lshlrev_b32_e32 v2, 14, v16
	v_and_b32_e32 v2, 0xffff8000, v2
	s_waitcnt vmcnt(8)
	s_barrier
	s_waitcnt vmcnt(6)
	v_lshl_add_u32 v2, v17, 11, v2
	v_and_b32_e32 v4, 1, v16
	v_lshl_or_b32 v2, v4, 6, v2
	v_bitop3_b32 v167, v19, s11, v13 bitop3:0xde
	s_mov_b32 s63, 0
	v_mov_b32_e32 v151, v3
	v_lshl_add_u32 v152, v18, 1, v2
	v_mov_b32_e32 v153, v3
	v_add_u32_e32 v169, 0, v22
	v_mov_b64_e32 v[154:155], s[78:79]
	s_barrier
	s_branch .LBB0_356

; #define PG8_STAGE(bufoff, gbase, voff) do { _Pragma("unroll") for (int _i = 0; _i < 2; ++_i) \
;         __builtin_amdgcn_global_load_lds((const unsigned*)((const char*)(gbase) + (voff)[_i]), (PG8_LAS unsigned*)(lds + (bufoff) + ldsw + _i * 8192), 16, 0, 0); } while (0)
; #define PG8_WAIT_V(n) asm volatile("s_waitcnt vmcnt(" #n ")" ::: "memory")
; #define PG8_BAR __builtin_amdgcn_s_barrier()
; template <class Epi, class Sched, bool ALIGN_EPI = false, bool SP2 = false>
; __device__ __forceinline__ void gemm_phase(PG8_LAS unsigned char* lds, const Gemm g, const Sched& S, const Epi& E, const int tid_arg) {
;     ...
;     if constexpr (SP2) {
;         PG8_STAGE(PG8_SB(0, 0), cB, voffB); PG8_STAGE(PG8_SB(0, 1), cB + hstep, voffB); PG8_STAGE(PG8_SA(0, 0), cA, voffA); PG8_STAGE(PG8_SA(0, 1), cA + hstep, voffA);
;         if (wr == 1) PG8_BAR;
;         PG8_WAIT_V(2); PG8_BAR;
;         PG8_STAGE(PG8_SB(1, 0), cB + kstep, voffB); PG8_STAGE(PG8_SA(1, 0), cA + kstep, voffA); PG8_STAGE(PG8_SB(1, 1), cB + hstep + kstep, voffB);
;         PG8_WAIT_V(6); PG8_BAR;
;     } else {
;         PG8_STAGE(PG8_SB(0, 0), cB, voffB); PG8_STAGE(PG8_SA(0, 0), cA, voffA); PG8_STAGE(PG8_SB(0, 1), cB + hstep, voffB); PG8_STAGE(PG8_SA(0, 1), cA + hstep, voffA);
;         if (wr == 1) PG8_BAR;
;         PG8_WAIT_V(4); PG8_BAR;
;         PG8_STAGE(PG8_SB(1, 0), cB + kstep, voffB); PG8_STAGE(PG8_SA(1, 0), cA + kstep, voffA); PG8_STAGE(PG8_SB(1, 1), cB + hstep + kstep, voffB);
;         PG8_WAIT_V(6); PG8_BAR;
;     }
.LBB0_754:
	v_lshrrev_b32_e32 v20, 1, v10
	v_and_b32_e32 v20, 24, v20
	s_lshl_b32 s10, s10, 5
	v_and_b32_e32 v11, 15, v10
	v_lshlrev_b32_e32 v21, 1, v20
	v_lshlrev_b32_e32 v10, 2, v10
	s_and_b32 s24, s10, 0x60
	v_lshl_add_u64 v[12:13], s[34:35], 0, v[2:3]
	v_mov_b32_e32 v133, v3
	v_lshl_or_b32 v152, s11, 6, v11
	v_lshl_or_b32 v11, v11, 6, v21
	s_lshl_b32 s11, s11, 13
	v_and_b32_e32 v10, 32, v10
	s_lshl_b32 s10, s24, 7
	v_lshl_add_u64 v[14:15], s[34:35], 0, v[132:133]
	v_mov_b32_e32 v137, v3
	v_bitop3_b32 v21, v11, s11, v10 bitop3:0xde
	v_bitop3_b32 v153, v11, s10, v10 bitop3:0xde
	s_add_i32 m0, s40, 0x18000
	v_lshl_add_u64 v[10:11], v[12:13], 0, s[76:77]
	v_lshl_add_u64 v[16:17], s[4:5], 0, v[136:137]
	v_mov_b32_e32 v135, v3
	global_load_lds_dwordx4 v[10:11], off
	v_lshl_add_u64 v[10:11], v[14:15], 0, s[76:77]
	s_add_i32 m0, s40, 0x1a000
	s_add_i32 s44, s40, 0x8000
	s_add_i32 s45, s40, 0xa000
	v_lshl_add_u64 v[18:19], s[4:5], 0, v[134:135]
	global_load_lds_dwordx4 v[10:11], off
	v_lshl_add_u64 v[10:11], v[16:17], 0, s[76:77]
	s_mov_b32 m0, s44
	s_add_u32 s10, s34, 0x40080
	global_load_lds_dwordx4 v[10:11], off
	v_lshl_add_u64 v[10:11], v[18:19], 0, s[76:77]
	s_mov_b32 m0, s45
	s_addc_u32 s11, s35, 0
	global_load_lds_dwordx4 v[10:11], off
	s_add_i32 m0, s40, 0x1c000
	v_lshl_add_u64 v[10:11], s[10:11], 0, v[2:3]
	global_load_lds_dwordx4 v[10:11], off
	v_lshl_add_u64 v[10:11], s[10:11], 0, v[132:133]
	s_add_i32 m0, s40, 0x1e000
	s_cmpk_lt_u32 s2, 0x100
	global_load_lds_dwordx4 v[10:11], off
	v_lshlrev_b32_e32 v10, 14, v8
	v_and_b32_e32 v10, 0xffff8000, v10
	v_lshl_add_u32 v7, v7, 11, v10
	v_and_b32_e32 v8, 1, v8
	v_lshl_or_b32 v7, v8, 6, v7
	v_lshl_add_u32 v138, v9, 1, v7
	v_lshlrev_b32_e32 v7, 14, v4
	v_and_b32_e32 v7, 0xffff8000, v7
	s_waitcnt vmcnt(8)
	s_barrier
	s_waitcnt vmcnt(6)
	v_lshl_add_u32 v5, v5, 11, v7
	v_and_b32_e32 v4, 1, v4
	v_lshl_or_b32 v4, v4, 6, v5
	v_readlane_b32 s10, v251, 17
	s_cselect_b64 s[22:23], -1, 0
	v_or_b32_e32 v154, s24, v20
	v_mov_b32_e32 v139, v3
	v_lshl_add_u32 v146, v6, 1, v4
	v_mov_b32_e32 v147, v3
	s_mov_b32 s46, 0
	v_add_u32_e32 v155, 0, v21
	v_readlane_b32 s2, v251, 16
	s_mov_b32 s47, s10
	s_barrier
	v_readlane_b32 s11, v251, 18
	s_branch .LBB0_757

; #define PG8_STAGE(bufoff, gbase, voff) do { _Pragma("unroll") for (int _i = 0; _i < 2; ++_i) \
;         __builtin_amdgcn_global_load_lds((const unsigned*)((const char*)(gbase) + (voff)[_i]), (PG8_LAS unsigned*)(lds + (bufoff) + ldsw + _i * 8192), 16, 0, 0); } while (0)
; #define PG8_WAIT_V(n) asm volatile("s_waitcnt vmcnt(" #n ")" ::: "memory")
; #define PG8_BAR __builtin_amdgcn_s_barrier()
; template <class Epi, class Sched, bool ALIGN_EPI = false, bool SP2 = false>
; __device__ __forceinline__ void gemm_phase(PG8_LAS unsigned char* lds, const Gemm g, const Sched& S, const Epi& E, const int tid_arg) {
;     ...
;     if constexpr (SP2) {
;         PG8_STAGE(PG8_SB(0, 0), cB, voffB); PG8_STAGE(PG8_SB(0, 1), cB + hstep, voffB); PG8_STAGE(PG8_SA(0, 0), cA, voffA); PG8_STAGE(PG8_SA(0, 1), cA + hstep, voffA);
;         if (wr == 1) PG8_BAR;
;         PG8_WAIT_V(2); PG8_BAR;
;         PG8_STAGE(PG8_SB(1, 0), cB + kstep, voffB); PG8_STAGE(PG8_SA(1, 0), cA + kstep, voffA); PG8_STAGE(PG8_SB(1, 1), cB + hstep + kstep, voffB);
;         PG8_WAIT_V(6); PG8_BAR;
;     } else {
;         PG8_STAGE(PG8_SB(0, 0), cB, voffB); PG8_STAGE(PG8_SA(0, 0), cA, voffA); PG8_STAGE(PG8_SB(0, 1), cB + hstep, voffB); PG8_STAGE(PG8_SA(0, 1), cA + hstep, voffA);
;         if (wr == 1) PG8_BAR;
;         PG8_WAIT_V(4); PG8_BAR;
;         PG8_STAGE(PG8_SB(1, 0), cB + kstep, voffB); PG8_STAGE(PG8_SA(1, 0), cA + kstep, voffA); PG8_STAGE(PG8_SB(1, 1), cB + hstep + kstep, voffB);
;         PG8_WAIT_V(6); PG8_BAR;
;     }
.LBB0_780:
	v_lshrrev_b32_e32 v20, 1, v18
	v_and_b32_e32 v20, 24, v20
	v_and_b32_e32 v19, 15, v18
	v_lshlrev_b32_e32 v21, 1, v20
	v_lshlrev_b32_e32 v18, 2, v18
	s_lshl_b32 s7, s7, 5
	v_lshl_or_b32 v150, s10, 6, v19
	v_lshl_or_b32 v19, v19, 6, v21
	s_lshl_b32 s10, s10, 13
	v_and_b32_e32 v18, 32, v18
	s_and_b32 s7, s7, 0x60
	v_bitop3_b32 v21, v19, s10, v18 bitop3:0xde
	s_lshl_b32 s10, s7, 7
	s_add_u32 s20, s2, 0x4800000
	s_addc_u32 s21, s3, 0
	s_add_i32 m0, s45, 0x18000
	v_lshl_add_u64 v[10:11], v[10:11], 0, s[76:77]
	global_load_lds_dwordx4 v[10:11], off
	v_lshl_add_u64 v[8:9], v[8:9], 0, s[76:77]
	s_add_i32 m0, s45, 0x1a000
	s_add_i32 s49, s45, 0x8000
	s_add_i32 s50, s45, 0xa000
	v_bitop3_b32 v151, v19, s10, v18 bitop3:0xde
	global_load_lds_dwordx4 v[8:9], off
	v_lshl_add_u64 v[4:5], v[4:5], 0, s[76:77]
	s_mov_b32 m0, s49
	s_add_u32 s10, s36, 0x40080
	global_load_lds_dwordx4 v[4:5], off
	v_lshl_add_u64 v[4:5], v[6:7], 0, s[76:77]
	s_mov_b32 m0, s50
	s_addc_u32 s11, s37, 0
	global_load_lds_dwordx4 v[4:5], off
	s_add_i32 m0, s45, 0x1c000
	v_lshl_add_u64 v[4:5], s[10:11], 0, v[2:3]
	global_load_lds_dwordx4 v[4:5], off
	v_lshl_add_u64 v[4:5], s[10:11], 0, v[132:133]
	s_add_i32 m0, s45, 0x1e000
	s_cmpk_lt_u32 s6, 0x100
	global_load_lds_dwordx4 v[4:5], off
	v_lshlrev_b32_e32 v4, 14, v16
	v_and_b32_e32 v4, 0xffff8000, v4
	v_lshl_add_u32 v4, v15, 11, v4
	v_and_b32_e32 v5, 1, v16
	v_lshl_or_b32 v4, v5, 6, v4
	v_lshl_add_u32 v138, v17, 1, v4
	v_lshlrev_b32_e32 v4, 14, v12
	v_and_b32_e32 v4, 0xffff8000, v4
	s_waitcnt vmcnt(8)
	s_barrier
	s_waitcnt vmcnt(6)
	v_lshl_add_u32 v4, v13, 11, v4
	v_and_b32_e32 v5, 1, v12
	v_lshl_or_b32 v4, v5, 6, v4
	v_readlane_b32 s10, v251, 17
	s_cselect_b64 s[22:23], -1, 0
	v_or_b32_e32 v152, s7, v20
	v_mov_b32_e32 v139, v3
	v_lshl_add_u32 v146, v14, 1, v4
	v_mov_b32_e32 v147, v3
	s_mov_b32 s51, 0
	v_add_u32_e32 v153, 0, v21
	v_readlane_b32 s6, v251, 16
	s_mov_b32 s7, s10
	s_barrier
	v_readlane_b32 s11, v251, 18
	s_branch .LBB0_783

; #define PG8_STAGE(bufoff, gbase, voff) do { _Pragma("unroll") for (int _i = 0; _i < 2; ++_i) \
;         __builtin_amdgcn_global_load_lds((const unsigned*)((const char*)(gbase) + (voff)[_i]), (PG8_LAS unsigned*)(lds + (bufoff) + ldsw + _i * 8192), 16, 0, 0); } while (0)
; #define PG8_WAIT_V(n) asm volatile("s_waitcnt vmcnt(" #n ")" ::: "memory")
; #define PG8_BAR __builtin_amdgcn_s_barrier()
; template <class Epi, class Sched, bool ALIGN_EPI = false, bool SP2 = false>
; __device__ __forceinline__ void gemm_phase(PG8_LAS unsigned char* lds, const Gemm g, const Sched& S, const Epi& E, const int tid_arg) {
;     ...
;     if constexpr (SP2) {
;         PG8_STAGE(PG8_SB(0, 0), cB, voffB); PG8_STAGE(PG8_SB(0, 1), cB + hstep, voffB); PG8_STAGE(PG8_SA(0, 0), cA, voffA); PG8_STAGE(PG8_SA(0, 1), cA + hstep, voffA);
;         if (wr == 1) PG8_BAR;
;         PG8_WAIT_V(2); PG8_BAR;
;         PG8_STAGE(PG8_SB(1, 0), cB + kstep, voffB); PG8_STAGE(PG8_SA(1, 0), cA + kstep, voffA); PG8_STAGE(PG8_SB(1, 1), cB + hstep + kstep, voffB);
;         PG8_WAIT_V(6); PG8_BAR;
;     } else {
;         PG8_STAGE(PG8_SB(0, 0), cB, voffB); PG8_STAGE(PG8_SA(0, 0), cA, voffA); PG8_STAGE(PG8_SB(0, 1), cB + hstep, voffB); PG8_STAGE(PG8_SA(0, 1), cA + hstep, voffA);
;         if (wr == 1) PG8_BAR;
;         PG8_WAIT_V(4); PG8_BAR;
;         PG8_STAGE(PG8_SB(1, 0), cB + kstep, voffB); PG8_STAGE(PG8_SA(1, 0), cA + kstep, voffA); PG8_STAGE(PG8_SB(1, 1), cB + hstep + kstep, voffB);
;         PG8_WAIT_V(6); PG8_BAR;
;     }
.LBB0_858:
	v_readlane_b32 s0, v250, 5
	s_add_u32 s13, s18, s0
	s_addc_u32 s14, s19, 0
	s_add_u32 s24, s13, 0x4780000
	s_addc_u32 s25, s14, 0
	v_readlane_b32 s0, v250, 6
	s_add_u32 s13, s18, s0
	s_addc_u32 s14, s19, 0
	v_bfe_u32 v19, v18, 4, 2
	s_add_u32 s26, s13, 0x8a88000
	v_and_b32_e32 v20, 15, v18
	v_lshlrev_b32_e32 v22, 4, v19
	v_lshlrev_b32_e32 v18, 2, v18
	s_addc_u32 s27, s14, 0
	s_and_b32 s55, s12, 3
	v_lshl_or_b32 v168, s7, 6, v20
	v_lshl_or_b32 v20, v20, 6, v22
	s_lshl_b32 s7, s7, 13
	v_and_b32_e32 v18, 32, v18
	s_add_i32 m0, s51, 0x18000
	v_lshl_add_u64 v[10:11], v[10:11], 0, s[76:77]
	v_bitop3_b32 v22, v20, s7, v18 bitop3:0xde
	s_lshl_b32 s7, s55, 12
	global_load_lds_dwordx4 v[10:11], off
	v_lshl_add_u64 v[8:9], v[8:9], 0, s[76:77]
	s_add_i32 m0, s51, 0x1a000
	s_add_i32 s56, s51, 0x8000
	s_add_i32 s57, s51, 0xa000
	global_load_lds_dwordx4 v[8:9], off
	v_lshl_add_u64 v[4:5], v[4:5], 0, s[76:77]
	s_mov_b32 m0, s56
	s_add_u32 s12, s42, 0x40080
	global_load_lds_dwordx4 v[4:5], off
	v_lshl_add_u64 v[4:5], v[6:7], 0, s[76:77]
	s_mov_b32 m0, s57
	s_addc_u32 s13, s43, 0
	global_load_lds_dwordx4 v[4:5], off
	s_add_i32 m0, s51, 0x1c000
	v_lshl_add_u64 v[4:5], s[12:13], 0, v[2:3]
	global_load_lds_dwordx4 v[4:5], off
	v_lshl_add_u64 v[4:5], s[12:13], 0, v[146:147]
	s_add_i32 m0, s51, 0x1e000
	v_lshlrev_b32_e32 v21, 3, v19
	global_load_lds_dwordx4 v[4:5], off
	v_lshlrev_b32_e32 v4, 14, v16
	v_and_b32_e32 v4, 0xffff8000, v4
	v_lshl_add_u32 v4, v15, 11, v4
	v_and_b32_e32 v5, 1, v16
	v_lshl_or_b32 v4, v5, 6, v4
	v_lshl_add_u32 v152, v17, 1, v4
	v_lshlrev_b32_e32 v4, 14, v12
	v_and_b32_e32 v4, 0xffff8000, v4
	s_waitcnt vmcnt(8)
	s_barrier
	s_waitcnt vmcnt(6)
	v_lshl_add_u32 v4, v13, 11, v4
	v_and_b32_e32 v5, 1, v12
	s_cmpk_lt_u32 s6, 0x100
	v_lshl_or_b32 v4, v5, 6, v4
	v_bitop3_b32 v169, v20, s7, v18 bitop3:0xde
	v_lshl_or_b32 v170, s55, 5, v21
	s_cselect_b64 s[28:29], -1, 0
	s_mov_b32 s58, 0
	v_cmp_eq_u32_e64 s[12:13], 0, v19
	v_or_b32_e32 v171, 16, v168
	v_or_b32_e32 v172, 32, v168
	v_or_b32_e32 v173, 48, v168
	v_add_u32_e32 v174, 0x80, v168
	v_add_u32_e32 v175, 0x90, v168
	v_add_u32_e32 v176, 0xa0, v168
	v_add_u32_e32 v177, 0xb0, v168
	v_mov_b32_e32 v153, v3
	v_lshl_add_u32 v154, v14, 1, v4
	v_mov_b32_e32 v155, v3
	v_add_u32_e32 v178, 0, v22
	v_readlane_b32 s6, v251, 16
	v_readlane_b32 s40, v251, 17
	s_barrier
	v_readlane_b32 s41, v251, 18
	s_branch .LBB0_861

; #define PG8_STAGE(bufoff, gbase, voff) do { _Pragma("unroll") for (int _i = 0; _i < 2; ++_i) \
;         __builtin_amdgcn_global_load_lds((const unsigned*)((const char*)(gbase) + (voff)[_i]), (PG8_LAS unsigned*)(lds + (bufoff) + ldsw + _i * 8192), 16, 0, 0); } while (0)
; #define PG8_WAIT_V(n) asm volatile("s_waitcnt vmcnt(" #n ")" ::: "memory")
; #define PG8_BAR __builtin_amdgcn_s_barrier()
; template <class Epi, class Sched, bool ALIGN_EPI = false, bool SP2 = false>
; __device__ __forceinline__ void gemm_phase(PG8_LAS unsigned char* lds, const Gemm g, const Sched& S, const Epi& E, const int tid_arg) {
;     ...
;     if constexpr (SP2) {
;         PG8_STAGE(PG8_SB(0, 0), cB, voffB); PG8_STAGE(PG8_SB(0, 1), cB + hstep, voffB); PG8_STAGE(PG8_SA(0, 0), cA, voffA); PG8_STAGE(PG8_SA(0, 1), cA + hstep, voffA);
;         if (wr == 1) PG8_BAR;
;         PG8_WAIT_V(2); PG8_BAR;
;         PG8_STAGE(PG8_SB(1, 0), cB + kstep, voffB); PG8_STAGE(PG8_SA(1, 0), cA + kstep, voffA); PG8_STAGE(PG8_SB(1, 1), cB + hstep + kstep, voffB);
;         PG8_WAIT_V(6); PG8_BAR;
;     } else {
;         PG8_STAGE(PG8_SB(0, 0), cB, voffB); PG8_STAGE(PG8_SA(0, 0), cA, voffA); PG8_STAGE(PG8_SB(0, 1), cB + hstep, voffB); PG8_STAGE(PG8_SA(0, 1), cA + hstep, voffA);
;         if (wr == 1) PG8_BAR;
;         PG8_WAIT_V(4); PG8_BAR;
;         PG8_STAGE(PG8_SB(1, 0), cB + kstep, voffB); PG8_STAGE(PG8_SA(1, 0), cA + kstep, voffA); PG8_STAGE(PG8_SB(1, 1), cB + hstep + kstep, voffB);
;         PG8_WAIT_V(6); PG8_BAR;
;     }
.LBB0_1070:
	s_add_u32 s6, s18, 0x8c90000
	s_addc_u32 s7, s19, 0
	s_lshl_b32 s12, s12, 5
	s_and_b32 s20, s12, 0x60
	s_mov_b64 s[12:13], 0x80
	s_add_i32 m0, s27, 0x18000
	v_lshl_add_u64 v[8:9], v[8:9], 0, s[12:13]
	s_lshl_b32 s15, s14, 13
	s_lshl_b32 s21, s20, 7
	global_load_lds_dwordx4 v[8:9], off
	v_lshl_add_u64 v[6:7], v[6:7], 0, s[12:13]
	s_add_i32 m0, s27, 0x1a000
	s_add_i32 s40, s27, 0x8000
	s_add_i32 s41, s27, 0xa000
	global_load_lds_dwordx4 v[6:7], off
	v_lshl_add_u64 v[2:3], v[2:3], 0, s[12:13]
	s_mov_b32 m0, s40
	s_add_u32 s16, s30, 0x40080
	global_load_lds_dwordx4 v[2:3], off
	v_lshl_add_u64 v[2:3], v[4:5], 0, s[12:13]
	s_mov_b32 m0, s41
	s_addc_u32 s17, s31, 0
	global_load_lds_dwordx4 v[2:3], off
	s_add_i32 m0, s27, 0x1c000
	v_lshl_add_u64 v[2:3], s[16:17], 0, v[132:133]
	global_load_lds_dwordx4 v[2:3], off
	v_lshl_add_u64 v[2:3], s[16:17], 0, v[136:137]
	s_add_i32 m0, s27, 0x1e000
	v_bfe_u32 v4, v10, 4, 2
	global_load_lds_dwordx4 v[2:3], off
	v_and_b32_e32 v3, 15, v10
	v_lshlrev_b32_e32 v2, 4, v4
	v_lshlrev_b32_e32 v5, 2, v10
	v_lshl_or_b32 v152, s14, 6, v3
	v_lshl_or_b32 v3, v3, 6, v2
	v_and_b32_e32 v5, 32, v5
	v_bitop3_b32 v6, v3, s15, v5 bitop3:0xde
	v_bitop3_b32 v153, v3, s21, v5 bitop3:0xde
	v_mov_b32_e32 v3, v133
	s_sext_i32_i8 s46, s10
	s_cmpk_lt_u32 s11, 0x100
	v_lshl_add_u64 v[2:3], s[18:19], 0, v[2:3]
	s_mov_b64 s[10:11], 0x8a88000
	v_lshl_add_u64 v[138:139], v[2:3], 0, s[10:11]
	v_lshlrev_b32_e32 v2, 14, v11
	v_and_b32_e32 v2, 0xffff8000, v2
	v_lshl_add_u32 v2, v12, 11, v2
	v_and_b32_e32 v3, 1, v11
	v_lshl_or_b32 v2, v3, 6, v2
	v_lshl_add_u32 v140, v13, 1, v2
	v_lshlrev_b32_e32 v2, 14, v14
	v_and_b32_e32 v2, 0xffff8000, v2
	s_waitcnt vmcnt(8)
	s_barrier
	s_waitcnt vmcnt(6)
	v_lshl_add_u32 v2, v15, 11, v2
	v_and_b32_e32 v3, 1, v14
	s_cselect_b64 s[14:15], -1, 0
	v_lshl_or_b32 v2, v3, 6, v2
	s_add_i32 s42, 0, 0x10000
	s_add_i32 s43, 0, 0x14000
	v_lshl_or_b32 v154, v4, 3, s20
	v_mov_b32_e32 v141, v133
	v_lshl_add_u32 v142, v16, 1, v2
	v_mov_b32_e32 v143, v133
	v_mov_b64_e32 v[144:145], 0xb2c
	v_mov_b64_e32 v[146:147], 0xb2b
	v_add_u32_e32 v155, s42, v153
	v_add_u32_e32 v156, s43, v153
	v_add_u32_e32 v157, 0, v6
	v_mov_b32_e32 v158, 0x358637bd
	s_mov_b32 s44, 0x800000
	s_movk_i32 s45, 0x1600
	s_barrier
	s_branch .LBB0_1073

; #define PG8_STAGE(bufoff, gbase, voff) do { _Pragma("unroll") for (int _i = 0; _i < 2; ++_i) \
;         __builtin_amdgcn_global_load_lds((const unsigned*)((const char*)(gbase) + (voff)[_i]), (PG8_LAS unsigned*)(lds + (bufoff) + ldsw + _i * 8192), 16, 0, 0); } while (0)
; #define PG8_WAIT_V(n) asm volatile("s_waitcnt vmcnt(" #n ")" ::: "memory")
; #define PG8_BAR __builtin_amdgcn_s_barrier()
; template <class Epi, class Sched, bool ALIGN_EPI = false, bool SP2 = false>
; __device__ __forceinline__ void gemm_phase(PG8_LAS unsigned char* lds, const Gemm g, const Sched& S, const Epi& E, const int tid_arg) {
;     ...
;     if constexpr (SP2) {
;         PG8_STAGE(PG8_SB(0, 0), cB, voffB); PG8_STAGE(PG8_SB(0, 1), cB + hstep, voffB); PG8_STAGE(PG8_SA(0, 0), cA, voffA); PG8_STAGE(PG8_SA(0, 1), cA + hstep, voffA);
;         if (wr == 1) PG8_BAR;
;         PG8_WAIT_V(2); PG8_BAR;
;         PG8_STAGE(PG8_SB(1, 0), cB + kstep, voffB); PG8_STAGE(PG8_SA(1, 0), cA + kstep, voffA); PG8_STAGE(PG8_SB(1, 1), cB + hstep + kstep, voffB);
;         PG8_WAIT_V(6); PG8_BAR;
;     } else {
;         PG8_STAGE(PG8_SB(0, 0), cB, voffB); PG8_STAGE(PG8_SA(0, 0), cA, voffA); PG8_STAGE(PG8_SB(0, 1), cB + hstep, voffB); PG8_STAGE(PG8_SA(0, 1), cA + hstep, voffA);
;         if (wr == 1) PG8_BAR;
;         PG8_WAIT_V(4); PG8_BAR;
;         PG8_STAGE(PG8_SB(1, 0), cB + kstep, voffB); PG8_STAGE(PG8_SA(1, 0), cA + kstep, voffA); PG8_STAGE(PG8_SB(1, 1), cB + hstep + kstep, voffB);
;         PG8_WAIT_V(6); PG8_BAR;
;     }
.LBB0_1156:
	s_add_u32 s14, s4, 0x4780000
	s_mov_b64 s[16:17], 0x80
	s_addc_u32 s15, s5, 0
	s_and_b32 s7, s7, 3
	s_add_i32 m0, s34, 0x18000
	v_lshl_add_u64 v[6:7], v[6:7], 0, s[16:17]
	s_lshl_b32 s19, s11, 13
	s_lshl_b32 s23, s7, 12
	global_load_lds_dwordx4 v[6:7], off
	v_lshl_add_u64 v[4:5], v[4:5], 0, s[16:17]
	s_add_i32 m0, s34, 0x1a000
	s_add_i32 s39, s34, 0x8000
	s_add_i32 s40, s34, 0xa000
	global_load_lds_dwordx4 v[4:5], off
	v_lshl_add_u64 v[0:1], v[0:1], 0, s[16:17]
	s_mov_b32 m0, s39
	s_add_u32 s20, s26, 0xb0080
	global_load_lds_dwordx4 v[0:1], off
	v_lshl_add_u64 v[0:1], v[2:3], 0, s[16:17]
	s_mov_b32 m0, s40
	s_addc_u32 s21, s27, 0
	global_load_lds_dwordx4 v[0:1], off
	s_add_i32 m0, s34, 0x1c000
	v_lshl_add_u64 v[0:1], s[20:21], 0, v[130:131]
	global_load_lds_dwordx4 v[0:1], off
	v_lshl_add_u64 v[0:1], s[20:21], 0, v[134:135]
	s_add_i32 m0, s34, 0x1e000
	s_cmpk_lt_u32 s10, 0x100
	global_load_lds_dwordx4 v[0:1], off
	v_bfe_u32 v0, v8, 4, 2
	v_and_b32_e32 v1, 15, v8
	v_lshlrev_b32_e32 v2, 3, v0
	v_lshlrev_b32_e32 v0, 4, v0
	v_lshl_or_b32 v146, s11, 6, v1
	v_lshl_or_b32 v0, v1, 6, v0
	v_lshlrev_b32_e32 v1, 2, v8
	v_and_b32_e32 v1, 32, v1
	v_bitop3_b32 v3, v0, s19, v1 bitop3:0xde
	v_bitop3_b32 v147, v0, s23, v1 bitop3:0xde
	v_lshl_or_b32 v148, s7, 5, v2
	v_lshrrev_b32_e32 v1, 1, v9
	v_mul_lo_u32 v0, v11, s6
	s_mov_b32 s7, 0xb000
	v_mad_u64_u32 v[0:1], s[10:11], v1, s7, v[0:1]
	v_or_b32_e32 v0, v0, v10
	s_mov_b64 s[20:21], 0xb0080
	v_add_lshl_u32 v0, v0, v12, 1
	v_mov_b32_e32 v1, v131
	v_lshl_add_u64 v[136:137], v[0:1], 0, s[20:21]
	v_lshrrev_b32_e32 v1, 1, v13
	v_mul_lo_u32 v0, v14, s6
	v_mad_u64_u32 v[0:1], s[6:7], v1, s7, v[0:1]
	s_waitcnt vmcnt(8)
	s_barrier
	s_waitcnt vmcnt(6)
	v_or_b32_e32 v0, v0, v15
	s_sext_i32_i8 s45, s18
	s_cselect_b64 s[18:19], -1, 0
	v_add_lshl_u32 v0, v0, v16, 1
	v_mov_b32_e32 v1, v131
	s_add_i32 s41, 0, 0x10000
	s_add_i32 s42, 0, 0x14000
	v_or_b32_e32 v149, 16, v146
	v_or_b32_e32 v150, 32, v146
	v_or_b32_e32 v151, 48, v146
	v_add_u32_e32 v152, 0x80, v146
	v_add_u32_e32 v153, 0x90, v146
	v_add_u32_e32 v154, 0xa0, v146
	v_add_u32_e32 v155, 0xb0, v146
	v_lshl_add_u64 v[138:139], v[0:1], 0, s[20:21]
	v_mov_b64_e32 v[140:141], 0x200
	v_mov_b64_e32 v[142:143], 0x1ff
	v_add_u32_e32 v156, s41, v147
	v_add_u32_e32 v157, s42, v147
	v_add_u32_e32 v158, 0, v3
	s_barrier
	s_branch .LBB0_1159
